# attnB loop: the four K fragment ds_read_b128 split over two MFMA gaps (2 after M2, 2 after M3) instead of one burst
# speedup vs baseline: 1.0036x; 1.0036x over previous
.Lb_loop:
	s_waitcnt lgkmcnt(0)
	v_mfma_f32_32x32x16_bf16 v[32:47], v[192:195], v[224:227], v[32:47]
	v_mfma_f32_32x32x16_bf16 v[48:63], v[196:199], v[224:227], v[48:63]
	ds_read_b128 v[96:99], v146 offset:33280
	ds_read_b128 v[100:103], v147 offset:33280
	v_mfma_f32_32x32x16_bf16 v[16:31], v[200:203], v[224:227], v[16:31]
	ds_read_b128 v[104:107], v148 offset:33280
	ds_read_b128 v[108:111], v149 offset:33280
	v_exp_f32_e32 v240, v80
	v_exp_f32_e32 v241, v81
	v_exp_f32_e32 v242, v82
	v_mfma_f32_32x32x16_bf16 v[0:15], v[204:207], v[224:227], v[0:15]
	v_exp_f32_e32 v243, v83
	v_exp_f32_e32 v244, v84
	v_exp_f32_e32 v245, v85
	s_waitcnt lgkmcnt(0)
	v_mfma_f32_32x32x16_bf16 v[112:127], v[96:99], v[128:131], v[64:79]
	ds_read_b128 v[96:99], v146 offset:37376
	ds_read_b64_tr_b16 v[192:193], v179 offset:18688
	ds_read_b64_tr_b16 v[194:195], v179 offset:19200
	v_add_f32_e32 v145, v240, v241
	v_cvt_pk_bf16_f32 v232, v240, v241
	v_exp_f32_e32 v246, v86
	v_exp_f32_e32 v247, v87
	v_mfma_f32_32x32x16_bf16 v[112:127], v[100:103], v[132:135], v[112:127]
	ds_read_b128 v[100:103], v147 offset:37376
	ds_read_b64_tr_b16 v[196:197], v179 offset:22848
	ds_read_b64_tr_b16 v[198:199], v179 offset:23360
	s_add_i32 s0, s50, 0xffff8000
	s_and_b32 s0, s0, 0x1f8000
	s_lshl_b32 s4, s0, 1
	s_add_i32 m0, s41, 0x18600
	s_nop 0
	buffer_load_dwordx4 v250, s[8:11], s4 offen lds
	s_add_i32 m0, s41, 0x1a600
	s_nop 0
	buffer_load_dwordx4 v250, s[8:11], s4 offen offset:128 lds
	v_add_f32_e32 v145, v145, v242
	v_add_f32_e32 v145, v145, v243
	v_cvt_pk_bf16_f32 v233, v242, v243
	v_exp_f32_e32 v240, v88
	v_mfma_f32_32x32x16_bf16 v[112:127], v[104:107], v[136:139], v[112:127]
	ds_read_b128 v[104:107], v148 offset:37376
	ds_read_b64_tr_b16 v[200:201], v179 offset:27008
	ds_read_b64_tr_b16 v[202:203], v179 offset:27520
	v_exp_f32_e32 v241, v89
	v_add_f32_e32 v145, v145, v244
	v_add_f32_e32 v145, v145, v245
	v_cvt_pk_bf16_f32 v234, v244, v245
	v_exp_f32_e32 v242, v90
	v_mfma_f32_32x32x16_bf16 v[112:127], v[108:111], v[140:143], v[112:127]
	ds_read_b128 v[108:111], v149 offset:37376
	ds_read_b64_tr_b16 v[204:205], v179 offset:31168
	ds_read_b64_tr_b16 v[206:207], v179 offset:31680
	s_add_i32 m0, s43, 0x18600
	s_nop 0
	buffer_load_dwordx4 v251, s[12:15], s4 offen lds
	s_add_i32 m0, s43, 0x1a600
	s_nop 0
	buffer_load_dwordx4 v251, s[12:15], s4 offen offset:128 lds
	v_exp_f32_e32 v243, v91
	v_add_f32_e32 v145, v145, v246
	v_add_f32_e32 v145, v145, v247
	v_cvt_pk_bf16_f32 v235, v246, v247
	v_mfma_f32_32x32x16_bf16 v[32:47], v[208:211], v[228:231], v[32:47]
	ds_read_b64_tr_b16 v[208:209], v179 offset:19712
	ds_read_b64_tr_b16 v[210:211], v179 offset:20224
	v_exp_f32_e32 v244, v92
	v_exp_f32_e32 v245, v93
	v_add_f32_e32 v145, v145, v240
	v_add_f32_e32 v145, v145, v241
	v_mfma_f32_32x32x16_bf16 v[48:63], v[212:215], v[228:231], v[48:63]
	ds_read_b64_tr_b16 v[212:213], v179 offset:23872
	ds_read_b64_tr_b16 v[214:215], v179 offset:24384
	v_cvt_pk_bf16_f32 v236, v240, v241
	v_exp_f32_e32 v246, v94
	v_exp_f32_e32 v247, v95
	v_mfma_f32_32x32x16_bf16 v[16:31], v[216:219], v[228:231], v[16:31]
	ds_read_b64_tr_b16 v[216:217], v179 offset:28032
	ds_read_b64_tr_b16 v[218:219], v179 offset:28544
	v_add_f32_e32 v145, v145, v242
	v_add_f32_e32 v145, v145, v243
	v_cvt_pk_bf16_f32 v237, v242, v243
	v_add_f32_e32 v145, v145, v244
	v_add_f32_e32 v145, v145, v245
	v_cvt_pk_bf16_f32 v238, v244, v245
	v_mfma_f32_32x32x16_bf16 v[0:15], v[220:223], v[228:231], v[0:15]
	ds_read_b64_tr_b16 v[220:221], v179 offset:32192
	ds_read_b64_tr_b16 v[222:223], v179 offset:32704
	v_add_f32_e32 v145, v145, v246
	v_add_f32_e32 v249, v145, v247
	v_cvt_pk_bf16_f32 v239, v246, v247
	v_add_f32_e32 v249, v248, v249
	v_cmp_lt_f32_e32 vcc, s3, v249
	v_add_f32_e32 v191, v191, v249
	s_waitcnt lgkmcnt(8)
	v_mfma_f32_32x32x16_bf16 v[80:95], v[96:99], v[128:131], v[64:79]
	v_exp_f32_e32 v240, v112
	v_exp_f32_e32 v241, v113
	v_exp_f32_e32 v242, v114
	v_mfma_f32_32x32x16_bf16 v[80:95], v[100:103], v[132:135], v[80:95]
	v_exp_f32_e32 v243, v115
	v_exp_f32_e32 v244, v116
	v_exp_f32_e32 v245, v117
	v_mfma_f32_32x32x16_bf16 v[80:95], v[104:107], v[136:139], v[80:95]
	v_add_f32_e32 v145, v240, v241
	v_cvt_pk_bf16_f32 v224, v240, v241
	v_exp_f32_e32 v246, v118
	v_mfma_f32_32x32x16_bf16 v[80:95], v[108:111], v[140:143], v[80:95]
	v_exp_f32_e32 v247, v119
	v_add_f32_e32 v145, v145, v242
	v_add_f32_e32 v145, v145, v243
	v_cvt_pk_bf16_f32 v225, v242, v243
	v_exp_f32_e32 v240, v120
	v_mfma_f32_32x32x16_bf16 v[32:47], v[192:195], v[232:235], v[32:47]
	ds_read_b64_tr_b16 v[192:193], v180 offset:0
	ds_read_b64_tr_b16 v[194:195], v180 offset:512
	v_exp_f32_e32 v241, v121
	v_add_f32_e32 v145, v145, v244
	v_add_f32_e32 v145, v145, v245
	v_cvt_pk_bf16_f32 v226, v244, v245
	v_mfma_f32_32x32x16_bf16 v[48:63], v[196:199], v[232:235], v[48:63]
	ds_read_b64_tr_b16 v[196:197], v180 offset:4160
	ds_read_b64_tr_b16 v[198:199], v180 offset:4672
	v_exp_f32_e32 v242, v122
	v_exp_f32_e32 v243, v123
	v_add_f32_e32 v145, v145, v246
	v_mfma_f32_32x32x16_bf16 v[16:31], v[200:203], v[232:235], v[16:31]
	ds_read_b64_tr_b16 v[200:201], v180 offset:8320
	ds_read_b64_tr_b16 v[202:203], v180 offset:8832
	v_add_f32_e32 v145, v145, v247
	v_cvt_pk_bf16_f32 v227, v246, v247
	v_exp_f32_e32 v244, v124
	v_exp_f32_e32 v245, v125
	v_mfma_f32_32x32x16_bf16 v[0:15], v[204:207], v[232:235], v[0:15]
	ds_read_b64_tr_b16 v[204:205], v180 offset:12480
	ds_read_b64_tr_b16 v[206:207], v180 offset:12992
	v_add_f32_e32 v145, v145, v240
	v_add_f32_e32 v145, v145, v241
	v_cvt_pk_bf16_f32 v228, v240, v241
	v_exp_f32_e32 v246, v126
	s_waitcnt lgkmcnt(8)
	v_mfma_f32_32x32x16_bf16 v[32:47], v[208:211], v[236:239], v[32:47]
	ds_read_b64_tr_b16 v[208:209], v180 offset:1024
	ds_read_b64_tr_b16 v[210:211], v180 offset:1536
	v_exp_f32_e32 v247, v127
	v_add_f32_e32 v145, v145, v242
	v_add_f32_e32 v145, v145, v243
	v_cvt_pk_bf16_f32 v229, v242, v243
	v_add_f32_e32 v145, v145, v244
	v_mfma_f32_32x32x16_bf16 v[48:63], v[212:215], v[236:239], v[48:63]
	ds_read_b64_tr_b16 v[212:213], v180 offset:5184
	ds_read_b64_tr_b16 v[214:215], v180 offset:5696
	v_add_f32_e32 v145, v145, v245
	v_cvt_pk_bf16_f32 v230, v244, v245
	v_add_f32_e32 v145, v145, v246
	v_add_f32_e32 v248, v145, v247
	v_cvt_pk_bf16_f32 v231, v246, v247
	v_mfma_f32_32x32x16_bf16 v[16:31], v[216:219], v[236:239], v[16:31]
	ds_read_b64_tr_b16 v[216:217], v180 offset:9344
	ds_read_b64_tr_b16 v[218:219], v180 offset:9856
	v_mfma_f32_32x32x16_bf16 v[0:15], v[220:223], v[236:239], v[0:15]
	ds_read_b64_tr_b16 v[220:221], v180 offset:13504
	ds_read_b64_tr_b16 v[222:223], v180 offset:14016
	s_cbranch_vccnz .Lb_rare0
.Lb_cont0:
	s_waitcnt vmcnt(4)
	s_barrier
	s_waitcnt lgkmcnt(0)
	v_mfma_f32_32x32x16_bf16 v[32:47], v[192:195], v[224:227], v[32:47]
	v_mfma_f32_32x32x16_bf16 v[48:63], v[196:199], v[224:227], v[48:63]
	ds_read_b128 v[96:99], v150 offset:0
	ds_read_b128 v[100:103], v151 offset:0
	v_mfma_f32_32x32x16_bf16 v[16:31], v[200:203], v[224:227], v[16:31]
	ds_read_b128 v[104:107], v152 offset:0
	ds_read_b128 v[108:111], v153 offset:0
	v_exp_f32_e32 v240, v80
	v_exp_f32_e32 v241, v81
	v_exp_f32_e32 v242, v82
	v_mfma_f32_32x32x16_bf16 v[0:15], v[204:207], v[224:227], v[0:15]
	v_exp_f32_e32 v243, v83
	v_exp_f32_e32 v244, v84
	v_exp_f32_e32 v245, v85
	s_waitcnt lgkmcnt(0)
	v_mfma_f32_32x32x16_bf16 v[112:127], v[96:99], v[128:131], v[64:79]
	ds_read_b128 v[96:99], v150 offset:4096
	ds_read_b64_tr_b16 v[192:193], v180 offset:2048
	ds_read_b64_tr_b16 v[194:195], v180 offset:2560
	v_add_f32_e32 v145, v240, v241
	v_cvt_pk_bf16_f32 v232, v240, v241
	v_exp_f32_e32 v246, v86
	v_exp_f32_e32 v247, v87
	v_mfma_f32_32x32x16_bf16 v[112:127], v[100:103], v[132:135], v[112:127]
	ds_read_b128 v[100:103], v151 offset:4096
	ds_read_b64_tr_b16 v[196:197], v180 offset:6208
	ds_read_b64_tr_b16 v[198:199], v180 offset:6720
	s_cmp_gt_u32 s6, 59
	s_cbranch_scc1 .Lb_pn0
	s_and_b32 s0, s50, 0x1f8000
	s_lshl_b32 s4, s0, 1
	s_add_i32 m0, s41, 0x0
	s_nop 0
	buffer_load_dwordx4 v250, s[8:11], s4 offen lds
	s_branch .Lb_po0

.Lb_cont1:
	s_waitcnt vmcnt(4)
	s_barrier
	s_waitcnt lgkmcnt(0)
	v_mfma_f32_32x32x16_bf16 v[32:47], v[192:195], v[224:227], v[32:47]
	v_mfma_f32_32x32x16_bf16 v[48:63], v[196:199], v[224:227], v[48:63]
	ds_read_b128 v[96:99], v150 offset:33280
	ds_read_b128 v[100:103], v151 offset:33280
	v_mfma_f32_32x32x16_bf16 v[16:31], v[200:203], v[224:227], v[16:31]
	ds_read_b128 v[104:107], v152 offset:33280
	ds_read_b128 v[108:111], v153 offset:33280
	v_exp_f32_e32 v240, v80
	v_exp_f32_e32 v241, v81
	v_exp_f32_e32 v242, v82
	v_mfma_f32_32x32x16_bf16 v[0:15], v[204:207], v[224:227], v[0:15]
	v_exp_f32_e32 v243, v83
	v_exp_f32_e32 v244, v84
	v_exp_f32_e32 v245, v85
	s_waitcnt lgkmcnt(0)
	v_mfma_f32_32x32x16_bf16 v[112:127], v[96:99], v[128:131], v[64:79]
	ds_read_b128 v[96:99], v150 offset:37376
	ds_read_b64_tr_b16 v[192:193], v182 offset:2048
	ds_read_b64_tr_b16 v[194:195], v182 offset:2560
	v_add_f32_e32 v145, v240, v241
	v_cvt_pk_bf16_f32 v232, v240, v241
	v_exp_f32_e32 v246, v86
	v_exp_f32_e32 v247, v87
	v_mfma_f32_32x32x16_bf16 v[112:127], v[100:103], v[132:135], v[112:127]
	ds_read_b128 v[100:103], v151 offset:37376
	ds_read_b64_tr_b16 v[196:197], v182 offset:6208
	ds_read_b64_tr_b16 v[198:199], v182 offset:6720
	s_cmp_gt_u32 s6, 59
	s_cbranch_scc1 .Lb_pn4
	s_add_i32 s0, s50, 0x8000
	s_and_b32 s0, s0, 0x1f8000
	s_lshl_b32 s4, s0, 1
	s_add_i32 m0, s41, 0x8200
	s_nop 0
	buffer_load_dwordx4 v250, s[8:11], s4 offen lds
	s_branch .Lb_po4

.Lb_cont2:
	s_waitcnt vmcnt(4)
	s_barrier
	s_cmp_gt_u32 s6, 59
	s_cbranch_scc1 .Lb_final
	s_waitcnt lgkmcnt(0)
	v_mfma_f32_32x32x16_bf16 v[32:47], v[192:195], v[224:227], v[32:47]
	v_mfma_f32_32x32x16_bf16 v[48:63], v[196:199], v[224:227], v[48:63]
	ds_read_b128 v[96:99], v146 offset:0
	ds_read_b128 v[100:103], v147 offset:0
	v_mfma_f32_32x32x16_bf16 v[16:31], v[200:203], v[224:227], v[16:31]
	ds_read_b128 v[104:107], v148 offset:0
	ds_read_b128 v[108:111], v149 offset:0
	v_exp_f32_e32 v240, v80
	v_exp_f32_e32 v241, v81
	v_exp_f32_e32 v242, v82
	v_mfma_f32_32x32x16_bf16 v[0:15], v[204:207], v[224:227], v[0:15]
	v_exp_f32_e32 v243, v83
	v_exp_f32_e32 v244, v84
	v_exp_f32_e32 v245, v85
	s_waitcnt lgkmcnt(0)
	v_mfma_f32_32x32x16_bf16 v[112:127], v[96:99], v[128:131], v[64:79]
	ds_read_b128 v[96:99], v146 offset:4096
	ds_read_b64_tr_b16 v[192:193], v182 offset:35328
	ds_read_b64_tr_b16 v[194:195], v182 offset:35840
	v_add_f32_e32 v145, v240, v241
	v_cvt_pk_bf16_f32 v232, v240, v241
	v_exp_f32_e32 v246, v86
	v_exp_f32_e32 v247, v87
	v_mfma_f32_32x32x16_bf16 v[112:127], v[100:103], v[132:135], v[112:127]
	ds_read_b128 v[100:103], v147 offset:4096
	ds_read_b64_tr_b16 v[196:197], v182 offset:39488
	ds_read_b64_tr_b16 v[198:199], v182 offset:40000
	s_add_i32 s0, s50, 0x10000
	s_and_b32 s0, s0, 0x1f8000
	s_lshl_b32 s4, s0, 1
	s_add_i32 m0, s41, 0x10400
	s_nop 0
	buffer_load_dwordx4 v250, s[8:11], s4 offen lds
	s_add_i32 m0, s41, 0x12400
	s_nop 0
	buffer_load_dwordx4 v250, s[8:11], s4 offen offset:128 lds
	v_add_f32_e32 v145, v145, v242
	v_add_f32_e32 v145, v145, v243
	v_cvt_pk_bf16_f32 v233, v242, v243
	v_exp_f32_e32 v240, v88
	v_mfma_f32_32x32x16_bf16 v[112:127], v[104:107], v[136:139], v[112:127]
	ds_read_b128 v[104:107], v148 offset:4096
	ds_read_b64_tr_b16 v[200:201], v182 offset:43648
	ds_read_b64_tr_b16 v[202:203], v182 offset:44160
	v_exp_f32_e32 v241, v89
	v_add_f32_e32 v145, v145, v244
	v_add_f32_e32 v145, v145, v245
	v_cvt_pk_bf16_f32 v234, v244, v245
	v_exp_f32_e32 v242, v90
	v_mfma_f32_32x32x16_bf16 v[112:127], v[108:111], v[140:143], v[112:127]
	ds_read_b128 v[108:111], v149 offset:4096
	ds_read_b64_tr_b16 v[204:205], v182 offset:47808
	ds_read_b64_tr_b16 v[206:207], v182 offset:48320
	s_add_i32 m0, s43, 0x10400
	s_nop 0
	buffer_load_dwordx4 v251, s[12:15], s4 offen lds
	s_add_i32 m0, s43, 0x12400
	s_nop 0
	buffer_load_dwordx4 v251, s[12:15], s4 offen offset:128 lds
	v_exp_f32_e32 v243, v91
	v_add_f32_e32 v145, v145, v246
	v_add_f32_e32 v145, v145, v247
	v_cvt_pk_bf16_f32 v235, v246, v247
	v_mfma_f32_32x32x16_bf16 v[32:47], v[208:211], v[228:231], v[32:47]
	ds_read_b64_tr_b16 v[208:209], v182 offset:36352
	ds_read_b64_tr_b16 v[210:211], v182 offset:36864
	v_exp_f32_e32 v244, v92
	v_exp_f32_e32 v245, v93
	v_add_f32_e32 v145, v145, v240
	v_add_f32_e32 v145, v145, v241
	v_mfma_f32_32x32x16_bf16 v[48:63], v[212:215], v[228:231], v[48:63]
	ds_read_b64_tr_b16 v[212:213], v182 offset:40512
	ds_read_b64_tr_b16 v[214:215], v182 offset:41024
	v_cvt_pk_bf16_f32 v236, v240, v241
	v_exp_f32_e32 v246, v94
	v_exp_f32_e32 v247, v95
	v_mfma_f32_32x32x16_bf16 v[16:31], v[216:219], v[228:231], v[16:31]
	ds_read_b64_tr_b16 v[216:217], v182 offset:44672
	ds_read_b64_tr_b16 v[218:219], v182 offset:45184
	v_add_f32_e32 v145, v145, v242
	v_add_f32_e32 v145, v145, v243
	v_cvt_pk_bf16_f32 v237, v242, v243
	v_add_f32_e32 v145, v145, v244
	v_add_f32_e32 v145, v145, v245
	v_cvt_pk_bf16_f32 v238, v244, v245
	v_mfma_f32_32x32x16_bf16 v[0:15], v[220:223], v[228:231], v[0:15]
	ds_read_b64_tr_b16 v[220:221], v182 offset:48832
	ds_read_b64_tr_b16 v[222:223], v182 offset:49344
	v_add_f32_e32 v145, v145, v246
	v_add_f32_e32 v249, v145, v247
	v_cvt_pk_bf16_f32 v239, v246, v247
	v_add_f32_e32 v249, v248, v249
	v_cmp_lt_f32_e32 vcc, s3, v249
	v_add_f32_e32 v191, v191, v249
	s_waitcnt lgkmcnt(8)
	v_mfma_f32_32x32x16_bf16 v[80:95], v[96:99], v[128:131], v[64:79]
	v_exp_f32_e32 v240, v112
	v_exp_f32_e32 v241, v113
	v_exp_f32_e32 v242, v114
	v_mfma_f32_32x32x16_bf16 v[80:95], v[100:103], v[132:135], v[80:95]
	v_exp_f32_e32 v243, v115
	v_exp_f32_e32 v244, v116
	v_exp_f32_e32 v245, v117
	v_mfma_f32_32x32x16_bf16 v[80:95], v[104:107], v[136:139], v[80:95]
	v_add_f32_e32 v145, v240, v241
	v_cvt_pk_bf16_f32 v224, v240, v241
	v_exp_f32_e32 v246, v118
	v_mfma_f32_32x32x16_bf16 v[80:95], v[108:111], v[140:143], v[80:95]
	v_exp_f32_e32 v247, v119
	v_add_f32_e32 v145, v145, v242
	v_add_f32_e32 v145, v145, v243
	v_cvt_pk_bf16_f32 v225, v242, v243
	v_exp_f32_e32 v240, v120
	v_mfma_f32_32x32x16_bf16 v[32:47], v[192:195], v[232:235], v[32:47]
	ds_read_b64_tr_b16 v[192:193], v179 offset:16640
	ds_read_b64_tr_b16 v[194:195], v179 offset:17152
	v_exp_f32_e32 v241, v121
	v_add_f32_e32 v145, v145, v244
	v_add_f32_e32 v145, v145, v245
	v_cvt_pk_bf16_f32 v226, v244, v245
	v_mfma_f32_32x32x16_bf16 v[48:63], v[196:199], v[232:235], v[48:63]
	ds_read_b64_tr_b16 v[196:197], v179 offset:20800
	ds_read_b64_tr_b16 v[198:199], v179 offset:21312
	v_exp_f32_e32 v242, v122
	v_exp_f32_e32 v243, v123
	v_add_f32_e32 v145, v145, v246
	v_mfma_f32_32x32x16_bf16 v[16:31], v[200:203], v[232:235], v[16:31]
	ds_read_b64_tr_b16 v[200:201], v179 offset:24960
	ds_read_b64_tr_b16 v[202:203], v179 offset:25472
	v_add_f32_e32 v145, v145, v247
	v_cvt_pk_bf16_f32 v227, v246, v247
	v_exp_f32_e32 v244, v124
	v_exp_f32_e32 v245, v125
	v_mfma_f32_32x32x16_bf16 v[0:15], v[204:207], v[232:235], v[0:15]
	ds_read_b64_tr_b16 v[204:205], v179 offset:29120
	ds_read_b64_tr_b16 v[206:207], v179 offset:29632
	v_add_f32_e32 v145, v145, v240
	v_add_f32_e32 v145, v145, v241
	v_cvt_pk_bf16_f32 v228, v240, v241
	v_exp_f32_e32 v246, v126
	s_waitcnt lgkmcnt(8)
	v_mfma_f32_32x32x16_bf16 v[32:47], v[208:211], v[236:239], v[32:47]
	ds_read_b64_tr_b16 v[208:209], v179 offset:17664
	ds_read_b64_tr_b16 v[210:211], v179 offset:18176
	v_exp_f32_e32 v247, v127
	v_add_f32_e32 v145, v145, v242
	v_add_f32_e32 v145, v145, v243
	v_cvt_pk_bf16_f32 v229, v242, v243
	v_add_f32_e32 v145, v145, v244
	v_mfma_f32_32x32x16_bf16 v[48:63], v[212:215], v[236:239], v[48:63]
	ds_read_b64_tr_b16 v[212:213], v179 offset:21824
	ds_read_b64_tr_b16 v[214:215], v179 offset:22336
	v_add_f32_e32 v145, v145, v245
	v_cvt_pk_bf16_f32 v230, v244, v245
	v_add_f32_e32 v145, v145, v246
	v_add_f32_e32 v248, v145, v247
	v_cvt_pk_bf16_f32 v231, v246, v247
	v_mfma_f32_32x32x16_bf16 v[16:31], v[216:219], v[236:239], v[16:31]
	ds_read_b64_tr_b16 v[216:217], v179 offset:25984
	ds_read_b64_tr_b16 v[218:219], v179 offset:26496
	v_mfma_f32_32x32x16_bf16 v[0:15], v[220:223], v[236:239], v[0:15]
	ds_read_b64_tr_b16 v[220:221], v179 offset:30144
	ds_read_b64_tr_b16 v[222:223], v179 offset:30656
	s_cbranch_vccnz .Lb_rare3
